# MLA attention tile loop hand-scheduled: QK split by key halves, exp/cvt/permlane interleaved under MFMAs, row sums accumulated in place, staging loads issued at tile start
# speedup vs baseline: 1.0406x; 1.0406x over previous
; #define SBAR() __builtin_amdgcn_sched_barrier(0)
; #define SLOAD2(k0) do { s_kn = *reinterpret_cast<const bf16x8*>(Kn + (size_t)((k0) + kn_r) * 1024 + kn_c); s_kr = *reinterpret_cast<const bf16x8*>(Kr + (size_t)((k0) + kr_r) * 32 + kr_c); \
;     s_v = *reinterpret_cast<const bf16x8*>(Vh + (size_t)((k0) + kn_r) * 1024 + kn_c); } while (0)
; __device__ __forceinline__ void attn_mla2(const bf16* __restrict__ Q0, const bf16* __restrict__ Q1, const bf16* __restrict__ Kn, const bf16* __restrict__ Kr, const bf16* __restrict__ Vh, ...
;     ...
;     for (int t = 0; t < NT; ++t) {
;         const char* buf = lds + cur;
;         f32x16 pa0 = f32x16{}, pa1 = f32x16{}, pb0 = f32x16{}, pb1 = f32x16{};
;         {
;             const char* kb = buf + KN_OFF + r32 * 144 + hi * 16; const char* kr = buf + KR_OFF + r32 * 80 + hi * 16;
;     ...
;             bf16x8 c0 = KLD0(0), c1 = KLD1(0);
; #pragma unroll
;             for (int d0 = 0; d0 < 6; ++d0) {
;                 bf16x8 n0 = c0, n1 = c1;
;                 if (d0 + 1 < 6) { n0 = KLD0(d0 + 1); n1 = KLD1(d0 + 1); }
;                 pa0 = __builtin_amdgcn_mfma_f32_32x32x16_bf16(c0, q0[d0], pa0, 0, 0, 0); pb0 = __builtin_amdgcn_mfma_f32_32x32x16_bf16(c0, q1[d0], pb0, 0, 0, 0);
;                 pa1 = __builtin_amdgcn_mfma_f32_32x32x16_bf16(c1, q0[d0], pa1, 0, 0, 0); pb1 = __builtin_amdgcn_mfma_f32_32x32x16_bf16(c1, q1[d0], pb1, 0, 0, 0);
;                 SBAR(); c0 = n0; c1 = n1;
;             }
;     ...
;         }
;         if (t + 1 < NT) SLOAD2((t + 1) * 64);
;         bf16x8 fa0, fa1, fa2, fa3, fb0, fb1, fb2, fb3;
;         {   float ps = 0.f;
; #pragma unroll
;             for (int r = 0; r < 16; ++r) { pa0[r] = __builtin_amdgcn_exp2f(pa0[r]); pa1[r] = __builtin_amdgcn_exp2f(pa1[r]);     ps += pa0[r] + pa1[r]; }
;             l0 += ps; PK4(pa0, 0, fa0); PK4(pa0, 8, fa1); PK4(pa1, 0, fa2); PK4(pa1, 8, fa3); }
;         {   float ps = 0.f;
; #pragma unroll
;             for (int r = 0; r < 16; ++r) { pb0[r] = __builtin_amdgcn_exp2f(pb0[r]); pb1[r] = __builtin_amdgcn_exp2f(pb1[r]); ps += pb0[r] + pb1[r]; }
;             l1 += ps; PK4(pb0, 0, fb0); PK4(pb0, 8, fb1); PK4(pb1, 0, fb2); PK4(pb1, 8, fb3); }
.LBB0_1629:
	s_add_i32 s12, s16, 0
	v_add3_u32 v184, s12, v246, v244
	v_add3_u32 v188, s12, v245, v244
	ds_read_b128 v[196:199], v184
	ds_read_b128 v[200:203], v184 offset:32
	ds_read_b128 v[204:207], v184 offset:64
	ds_read_b128 v[208:211], v184 offset:96
	ds_read_b128 v[212:215], v188 offset:9216
	ds_read_b128 v[216:219], v188 offset:9248
	ds_read_b128 v[220:223], v184 offset:4608
	ds_read_b128 v[224:227], v184 offset:4640
	ds_read_b128 v[228:231], v184 offset:4672
	ds_read_b128 v[232:235], v184 offset:4704
	ds_read_b128 v[236:239], v188 offset:11776
	ds_read_b128 v[250:253], v188 offset:11808
	v_lshl_add_u64 v[176:177], v[194:195], 0, s[2:3]
	s_mov_b32 s12, 0x8e20000
	v_add_co_u32_e32 v178, vcc, s12, v176
	s_mov_b32 s12, 0xae20000
	s_nop 0
	v_addc_co_u32_e32 v179, vcc, 0, v177, vcc
	v_add_co_u32_e32 v176, vcc, s12, v176
	s_nop 1
	v_addc_co_u32_e32 v177, vcc, 0, v177, vcc
	global_load_dwordx4 v[180:183], v[178:179], off
	global_load_dwordx4 v[176:179], v[176:177], off
	v_lshl_add_u64 v[186:187], v[192:193], 0, s[2:3]
	global_load_dwordx2 v[186:187], v[186:187], off
	s_waitcnt lgkmcnt(11)
	v_mfma_f32_32x32x16_bf16 v[96:111], v[196:199], v[160:163], 0
	s_sub_i32 s15, 0, s16
	v_ashrrev_i32_e32 v80, 3, v241
	v_and_b32_e32 v81, 7, v241
	s_waitcnt lgkmcnt(10)
	v_mfma_f32_32x32x16_bf16 v[96:111], v[200:203], v[168:171], v[96:111]
	v_lshlrev_b32_e32 v82, 4, v81
	v_mul_u32_u24_e32 v184, 0x90, v80
	v_add3_u32 v184, s15, v184, v82
	s_waitcnt lgkmcnt(9)
	v_mfma_f32_32x32x16_bf16 v[96:111], v[204:207], v[156:159], v[96:111]
	v_mul_u32_u24_e32 v189, 0x50, v80
	v_lshlrev_b32_e32 v83, 3, v81
	v_add3_u32 v189, s15, v189, v83
	s_waitcnt lgkmcnt(8)
	v_mfma_f32_32x32x16_bf16 v[96:111], v[208:211], v[144:147], v[96:111]
	v_bfe_u32 v83, v241, 3, 2
	v_and_b32_e32 v82, 48, v82
	v_lshlrev_b32_e32 v84, 1, v80
	s_waitcnt lgkmcnt(7)
	v_mfma_f32_32x32x16_bf16 v[96:111], v[212:215], v[140:143], v[96:111]
	v_and_b32_e32 v85, 0x1fffff0, v80
	v_and_b32_e32 v84, 8, v84
	v_or3_b32 v81, v84, v85, v81
	s_waitcnt lgkmcnt(6)
	v_mfma_f32_32x32x16_bf16 v[96:111], v[216:219], v[128:131], v[96:111]
	v_lshrrev_b32_e32 v80, 1, v80
	v_lshlrev_b32_e32 v81, 7, v81
	v_and_b32_e32 v81, 0xfffffe00, v81
	v_and_or_b32 v83, v80, 4, v83
	v_lshlrev_b32_e32 v83, 6, v83
	v_mfma_f32_32x32x16_bf16 v[64:79], v[196:199], v[164:167], 0
	v_add_u32_e32 v80, s15, v81
	v_add3_u32 v188, v80, v83, v82
	v_lshl_add_u64 v[192:193], v[192:193], 0, s[30:31]
	v_lshl_add_u64 v[194:195], v[194:195], 0, s[36:37]
	s_nop 0
	v_mfma_f32_32x32x16_bf16 v[64:79], v[200:203], v[172:175], v[64:79]
	v_exp_f32_e32 v96, v96
	v_exp_f32_e32 v97, v97
	v_add_f32_e32 v190, v190, v96
	v_exp_f32_e32 v98, v98
	v_add_f32_e32 v190, v190, v97
	v_mfma_f32_32x32x16_bf16 v[64:79], v[204:207], v[152:155], v[64:79]
	v_exp_f32_e32 v99, v99
	v_add_f32_e32 v190, v190, v98
	v_exp_f32_e32 v100, v100
	v_add_f32_e32 v190, v190, v99
	v_exp_f32_e32 v101, v101
	v_mfma_f32_32x32x16_bf16 v[64:79], v[208:211], v[148:151], v[64:79]
	v_add_f32_e32 v190, v190, v100
	v_exp_f32_e32 v102, v102
	v_add_f32_e32 v190, v190, v101
	v_exp_f32_e32 v103, v103
	v_add_f32_e32 v190, v190, v102
	v_exp_f32_e32 v104, v104
	v_mfma_f32_32x32x16_bf16 v[64:79], v[212:215], v[136:139], v[64:79]
	v_add_f32_e32 v190, v190, v103
	v_exp_f32_e32 v105, v105
	v_add_f32_e32 v190, v190, v104
	v_exp_f32_e32 v106, v106
	v_add_f32_e32 v190, v190, v105
	v_mfma_f32_32x32x16_bf16 v[64:79], v[216:219], v[132:135], v[64:79]
	v_exp_f32_e32 v107, v107
	v_add_f32_e32 v190, v190, v106
	v_exp_f32_e32 v108, v108
	v_add_f32_e32 v190, v190, v107
	v_exp_f32_e32 v109, v109
	v_add_u32_e32 v212, s16, v248
	s_waitcnt lgkmcnt(5)
	v_mfma_f32_32x32x16_bf16 v[112:127], v[220:223], v[160:163], 0
	v_add_f32_e32 v190, v190, v108
	v_exp_f32_e32 v110, v110
	v_add_f32_e32 v190, v190, v109
	v_exp_f32_e32 v111, v111
	v_add_f32_e32 v190, v190, v110
	v_add_f32_e32 v190, v190, v111
	s_waitcnt lgkmcnt(4)
	v_mfma_f32_32x32x16_bf16 v[112:127], v[224:227], v[168:171], v[112:127]
	v_exp_f32_e32 v64, v64
	v_exp_f32_e32 v65, v65
	v_add_f32_e32 v191, v191, v64
	v_exp_f32_e32 v66, v66
	v_add_f32_e32 v191, v191, v65
	s_waitcnt lgkmcnt(3)
	v_mfma_f32_32x32x16_bf16 v[112:127], v[228:231], v[156:159], v[112:127]
	v_exp_f32_e32 v67, v67
	v_add_f32_e32 v191, v191, v66
	v_exp_f32_e32 v68, v68
	v_add_f32_e32 v191, v191, v67
	v_exp_f32_e32 v69, v69
	s_waitcnt lgkmcnt(2)
	v_mfma_f32_32x32x16_bf16 v[112:127], v[232:235], v[144:147], v[112:127]
	v_add_f32_e32 v191, v191, v68
	v_exp_f32_e32 v70, v70
	v_add_f32_e32 v191, v191, v69
	v_exp_f32_e32 v71, v71
	v_add_f32_e32 v191, v191, v70
	v_exp_f32_e32 v72, v72
	s_waitcnt lgkmcnt(1)
	v_mfma_f32_32x32x16_bf16 v[112:127], v[236:239], v[140:143], v[112:127]
	v_add_f32_e32 v191, v191, v71
	v_exp_f32_e32 v73, v73
	v_add_f32_e32 v191, v191, v72
	v_exp_f32_e32 v74, v74
	v_add_f32_e32 v191, v191, v73
	s_waitcnt lgkmcnt(0)
; template <int DVB> __device__ __forceinline__ int v_st(int k, int c) { const int kk = (k & ~0xC) | ((k & 4) << 1) | ((k & 8) >> 1); return ((kk >> 3) * DVB + (c >> 5)) * 512 + ((kk & 7) * 32 + (c & 31)) * 2; }
; __device__ __forceinline__ void attn_mla2(const bf16* __restrict__ Q0, const bf16* __restrict__ Q1, const bf16* __restrict__ Kn, const bf16* __restrict__ Kr, const bf16* __restrict__ Vh, ...
;     ...
;         {   float ps = 0.f;
; #pragma unroll
;             for (int r = 0; r < 16; ++r) { pa0[r] = __builtin_amdgcn_exp2f(pa0[r]); pa1[r] = __builtin_amdgcn_exp2f(pa1[r]);     ps += pa0[r] + pa1[r]; }
;             l0 += ps; PK4(pa0, 0, fa0); PK4(pa0, 8, fa1); PK4(pa1, 0, fa2); PK4(pa1, 8, fa3); }
;         {   float ps = 0.f;
; #pragma unroll
;             for (int r = 0; r < 16; ++r) { pb0[r] = __builtin_amdgcn_exp2f(pb0[r]); pb1[r] = __builtin_amdgcn_exp2f(pb1[r]); ps += pb0[r] + pb1[r]; }
;             l1 += ps; PK4(pb0, 0, fb0); PK4(pb0, 8, fb1); PK4(pb1, 0, fb2); PK4(pb1, 8, fb3); }
;         {   const int vb = vb0 + cur;
;     ...
;             PV2(0); PV2(1);
;     ...
;         }
;         if (t + 1 < NT) {
;             int tw = tid; asm volatile("" : "+v"(tw));
;             char* bb_ = lds + (BUF - cur);
;             *reinterpret_cast<bf16x8*>(bb_ + KN_OFF + (tw >> 3) * 144 + (tw & 7) * 16) = s_kn;
;             if (tw < 256) *reinterpret_cast<bf16x8*>(bb_ + KR_OFF + ((tw >> 2) & 63) * 80 + (tw & 3) * 16) = s_kr;
;             *reinterpret_cast<bf16x8*>(bb_ + V_OFF + v_st<2>(tw >> 3, (tw & 7) * 8)) = s_v;
;         }
;         __syncthreads();
;         cur = BUF - cur;
	v_mfma_f32_32x32x16_bf16 v[112:127], v[250:253], v[128:131], v[112:127]
	v_exp_f32_e32 v75, v75
	v_add_f32_e32 v191, v191, v74
	v_exp_f32_e32 v76, v76
	v_add_f32_e32 v191, v191, v75
	v_exp_f32_e32 v77, v77
	v_mfma_f32_32x32x16_bf16 v[80:95], v[220:223], v[164:167], 0
	v_add_f32_e32 v191, v191, v76
	v_exp_f32_e32 v78, v78
	v_add_f32_e32 v191, v191, v77
	v_exp_f32_e32 v79, v79
	v_add_f32_e32 v191, v191, v78
	v_add_f32_e32 v191, v191, v79
	v_mfma_f32_32x32x16_bf16 v[80:95], v[224:227], v[172:175], v[80:95]
	v_cvt_pk_bf16_f32 v196, v96, v97
	v_cvt_pk_bf16_f32 v197, v98, v99
	v_cvt_pk_bf16_f32 v198, v100, v101
	v_cvt_pk_bf16_f32 v199, v102, v103
	v_cvt_pk_bf16_f32 v200, v104, v105
	v_cvt_pk_bf16_f32 v201, v106, v107
	v_cvt_pk_bf16_f32 v202, v108, v109
	v_cvt_pk_bf16_f32 v203, v110, v111
	v_mfma_f32_32x32x16_bf16 v[80:95], v[228:231], v[152:155], v[80:95]
	ds_read_b64_tr_b16 v[96:97], v212 offset:0
	ds_read_b64_tr_b16 v[98:99], v212 offset:1024
	ds_read_b64_tr_b16 v[100:101], v212 offset:2048
	ds_read_b64_tr_b16 v[102:103], v212 offset:3072
	ds_read_b64_tr_b16 v[104:105], v212 offset:512
	ds_read_b64_tr_b16 v[106:107], v212 offset:1536
	ds_read_b64_tr_b16 v[108:109], v212 offset:2560
	ds_read_b64_tr_b16 v[110:111], v212 offset:3584
	v_permlane32_swap_b32_e32 v196, v198
	v_permlane32_swap_b32_e32 v197, v199
	v_permlane32_swap_b32_e32 v200, v202
	v_permlane32_swap_b32_e32 v201, v203
	v_mfma_f32_32x32x16_bf16 v[80:95], v[232:235], v[148:151], v[80:95]
	v_cvt_pk_bf16_f32 v204, v64, v65
	v_cvt_pk_bf16_f32 v205, v66, v67
	v_cvt_pk_bf16_f32 v206, v68, v69
	v_cvt_pk_bf16_f32 v207, v70, v71
	v_cvt_pk_bf16_f32 v208, v72, v73
	v_cvt_pk_bf16_f32 v209, v74, v75
	v_cvt_pk_bf16_f32 v210, v76, v77
	v_cvt_pk_bf16_f32 v211, v78, v79
	v_mfma_f32_32x32x16_bf16 v[80:95], v[236:239], v[136:139], v[80:95]
	ds_read_b64_tr_b16 v[64:65], v212 offset:4096
	ds_read_b64_tr_b16 v[66:67], v212 offset:5120
	ds_read_b64_tr_b16 v[68:69], v212 offset:6144
	ds_read_b64_tr_b16 v[70:71], v212 offset:7168
	ds_read_b64_tr_b16 v[72:73], v212 offset:4608
	ds_read_b64_tr_b16 v[74:75], v212 offset:5632
	ds_read_b64_tr_b16 v[76:77], v212 offset:6656
	ds_read_b64_tr_b16 v[78:79], v212 offset:7680
	v_permlane32_swap_b32_e32 v204, v206
	v_permlane32_swap_b32_e32 v205, v207
	v_permlane32_swap_b32_e32 v208, v210
	v_permlane32_swap_b32_e32 v209, v211
	v_mfma_f32_32x32x16_bf16 v[80:95], v[250:253], v[132:135], v[80:95]
	v_exp_f32_e32 v112, v112
	v_exp_f32_e32 v113, v113
	v_add_f32_e32 v190, v190, v112
	v_exp_f32_e32 v114, v114
	v_add_f32_e32 v190, v190, v113
	s_waitcnt lgkmcnt(8)
	v_mfma_f32_32x32x16_bf16 v[0:15], v[196:199], v[96:99], v[0:15]
	v_exp_f32_e32 v115, v115
	v_add_f32_e32 v190, v190, v114
	v_exp_f32_e32 v116, v116
	v_add_f32_e32 v190, v190, v115
	v_exp_f32_e32 v117, v117
	v_mfma_f32_32x32x16_bf16 v[32:47], v[204:207], v[96:99], v[32:47]
	v_add_f32_e32 v190, v190, v116
	v_exp_f32_e32 v118, v118
	v_add_f32_e32 v190, v190, v117
	v_exp_f32_e32 v119, v119
	v_add_f32_e32 v190, v190, v118
	v_exp_f32_e32 v120, v120
	v_mfma_f32_32x32x16_bf16 v[16:31], v[196:199], v[104:107], v[16:31]
	v_add_f32_e32 v190, v190, v119
	v_exp_f32_e32 v121, v121
	v_add_f32_e32 v190, v190, v120
	v_exp_f32_e32 v122, v122
	v_add_f32_e32 v190, v190, v121
	v_mfma_f32_32x32x16_bf16 v[48:63], v[204:207], v[104:107], v[48:63]
	v_exp_f32_e32 v123, v123
	v_add_f32_e32 v190, v190, v122
	v_exp_f32_e32 v124, v124
	v_add_f32_e32 v190, v190, v123
	v_exp_f32_e32 v125, v125
	v_mfma_f32_32x32x16_bf16 v[0:15], v[200:203], v[100:103], v[0:15]
	v_add_f32_e32 v190, v190, v124
	v_exp_f32_e32 v126, v126
	v_add_f32_e32 v190, v190, v125
	v_exp_f32_e32 v127, v127
	v_add_f32_e32 v190, v190, v126
	v_add_f32_e32 v190, v190, v127
	v_mfma_f32_32x32x16_bf16 v[32:47], v[208:211], v[100:103], v[32:47]
	v_cvt_pk_bf16_f32 v220, v112, v113
	v_cvt_pk_bf16_f32 v221, v114, v115
	v_cvt_pk_bf16_f32 v222, v116, v117
	v_cvt_pk_bf16_f32 v223, v118, v119
	v_cvt_pk_bf16_f32 v224, v120, v121
	v_cvt_pk_bf16_f32 v225, v122, v123
	v_cvt_pk_bf16_f32 v226, v124, v125
	v_cvt_pk_bf16_f32 v227, v126, v127
	v_mfma_f32_32x32x16_bf16 v[16:31], v[200:203], v[108:111], v[16:31]
	v_permlane32_swap_b32_e32 v220, v222
	v_permlane32_swap_b32_e32 v221, v223
	v_permlane32_swap_b32_e32 v224, v226
	v_permlane32_swap_b32_e32 v225, v227
	v_exp_f32_e32 v80, v80
	v_exp_f32_e32 v81, v81
	v_add_f32_e32 v191, v191, v80
	v_exp_f32_e32 v82, v82
	v_mfma_f32_32x32x16_bf16 v[48:63], v[208:211], v[108:111], v[48:63]
	v_add_f32_e32 v191, v191, v81
	v_exp_f32_e32 v83, v83
	v_add_f32_e32 v191, v191, v82
	v_exp_f32_e32 v84, v84
	v_add_f32_e32 v191, v191, v83
	s_waitcnt lgkmcnt(0)
	v_mfma_f32_32x32x16_bf16 v[0:15], v[220:223], v[64:67], v[0:15]
	v_exp_f32_e32 v85, v85
	v_add_f32_e32 v191, v191, v84
	v_exp_f32_e32 v86, v86
	v_add_f32_e32 v191, v191, v85
	v_exp_f32_e32 v87, v87
	v_add_f32_e32 v191, v191, v86
	v_mfma_f32_32x32x16_bf16 v[16:31], v[220:223], v[72:75], v[16:31]
	v_exp_f32_e32 v88, v88
	v_add_f32_e32 v191, v191, v87
	v_exp_f32_e32 v89, v89
	v_add_f32_e32 v191, v191, v88
	v_exp_f32_e32 v90, v90
	v_mfma_f32_32x32x16_bf16 v[0:15], v[224:227], v[68:71], v[0:15]
	v_add_f32_e32 v191, v191, v89
	v_exp_f32_e32 v91, v91
	v_add_f32_e32 v191, v191, v90
	v_exp_f32_e32 v92, v92
	v_add_f32_e32 v191, v191, v91
	v_exp_f32_e32 v93, v93
	v_mfma_f32_32x32x16_bf16 v[16:31], v[224:227], v[76:79], v[16:31]
	v_add_f32_e32 v191, v191, v92
	v_exp_f32_e32 v94, v94
	v_add_f32_e32 v191, v191, v93
	v_exp_f32_e32 v95, v95
	v_add_f32_e32 v191, v191, v94
	v_add_f32_e32 v191, v191, v95
	v_cvt_pk_bf16_f32 v228, v80, v81
	v_cvt_pk_bf16_f32 v229, v82, v83
	v_cvt_pk_bf16_f32 v230, v84, v85
	v_cvt_pk_bf16_f32 v231, v86, v87
	v_cvt_pk_bf16_f32 v232, v88, v89
	v_cvt_pk_bf16_f32 v233, v90, v91
	v_cvt_pk_bf16_f32 v234, v92, v93
	v_cvt_pk_bf16_f32 v235, v94, v95
	s_waitcnt vmcnt(0)
	ds_write_b128 v184, v[180:183] offset:30976
	ds_write_b128 v188, v[176:179] offset:45312
	ds_write_b64 v189, v[186:187] offset:40192
	v_permlane32_swap_b32_e32 v228, v230
	v_permlane32_swap_b32_e32 v229, v231
	v_permlane32_swap_b32_e32 v232, v234
	v_permlane32_swap_b32_e32 v233, v235
	s_sub_i32 s16, 0x7900, s16
	s_add_i32 s14, s14, -1
	s_cmp_eq_u32 s14, 0
	v_mfma_f32_32x32x16_bf16 v[32:47], v[228:231], v[64:67], v[32:47]
	v_mfma_f32_32x32x16_bf16 v[48:63], v[228:231], v[72:75], v[48:63]
	v_mfma_f32_32x32x16_bf16 v[32:47], v[232:235], v[68:71], v[32:47]
	v_mfma_f32_32x32x16_bf16 v[48:63], v[232:235], v[76:79], v[48:63]
	s_waitcnt lgkmcnt(0)
	s_barrier
	s_cbranch_scc1 .LBB0_1633
	v_mov_b32_e32 v240, 0x358637bd
	s_branch .LBB0_1629
